# combination + accumulator clear with 64 v_mov_b64 instead of 128 v_mov_b32 before each GEMM unit (P2,P5,P7,P11)
# speedup vs baseline: 1.0005x; 1.0005x over previous
.LBB0_211:
	s_lshl_b32 s28, s72, 8
	s_ashr_i32 s29, s28, 31
	s_lshl_b64 s[28:29], s[28:29], 11
	s_add_u32 s28, s94, s28
	s_addc_u32 s29, s95, s29
	s_and_b64 s[30:31], s[4:5], exec
	s_cselect_b32 s40, s29, s1
	s_cselect_b32 s41, s28, s0
	s_ashr_i32 s27, s26, 31
	s_lshl_b64 s[30:31], s[26:27], 19
	s_add_u32 s30, s10, s30
	s_addc_u32 s31, s11, s31
	s_and_b64 s[38:39], s[4:5], exec
	s_cselect_b32 s27, s31, s37
	s_cselect_b32 s42, s30, s36
	s_add_u32 s0, s0, 0x40080
	s_addc_u32 s1, s1, 0
	s_add_u32 s43, s36, 0x100
	v_mov_b64_e32 v[0:1], 0
	s_addc_u32 s44, s37, 0
	s_mov_b32 s45, -2
	v_mov_b64_e32 v[2:3], 0
	v_mov_b64_e32 v[4:5], 0
	v_mov_b64_e32 v[6:7], 0
	v_mov_b64_e32 v[8:9], 0
	v_mov_b64_e32 v[10:11], 0
	v_mov_b64_e32 v[20:21], 0
	v_mov_b64_e32 v[22:23], 0
	v_mov_b64_e32 v[24:25], 0
	v_mov_b64_e32 v[26:27], 0
	v_mov_b64_e32 v[36:37], 0
	v_mov_b64_e32 v[38:39], 0
	v_mov_b64_e32 v[40:41], 0
	v_mov_b64_e32 v[42:43], 0
	v_mov_b64_e32 v[52:53], 0
	v_mov_b64_e32 v[54:55], 0
	v_mov_b64_e32 v[12:13], 0
	v_mov_b64_e32 v[14:15], 0
	v_mov_b64_e32 v[16:17], 0
	v_mov_b64_e32 v[18:19], 0
	v_mov_b64_e32 v[28:29], 0
	v_mov_b64_e32 v[30:31], 0
	v_mov_b64_e32 v[32:33], 0
	v_mov_b64_e32 v[34:35], 0
	v_mov_b64_e32 v[44:45], 0
	v_mov_b64_e32 v[46:47], 0
	v_mov_b64_e32 v[48:49], 0
	v_mov_b64_e32 v[50:51], 0
	v_mov_b64_e32 v[56:57], 0
	v_mov_b64_e32 v[58:59], 0
	v_mov_b64_e32 v[60:61], 0
	v_mov_b64_e32 v[62:63], 0
	v_mov_b64_e32 v[64:65], 0
	v_mov_b64_e32 v[66:67], 0
	v_mov_b64_e32 v[68:69], 0
	v_mov_b64_e32 v[70:71], 0
	v_mov_b64_e32 v[76:77], 0
	v_mov_b64_e32 v[78:79], 0
	v_mov_b64_e32 v[84:85], 0
	v_mov_b64_e32 v[86:87], 0
	v_mov_b64_e32 v[92:93], 0
	v_mov_b64_e32 v[94:95], 0
	v_mov_b64_e32 v[100:101], 0
	v_mov_b64_e32 v[102:103], 0
	v_mov_b64_e32 v[108:109], 0
	v_mov_b64_e32 v[110:111], 0
	v_mov_b64_e32 v[116:117], 0
	v_mov_b64_e32 v[118:119], 0
	v_mov_b64_e32 v[72:73], 0
	v_mov_b64_e32 v[74:75], 0
	v_mov_b64_e32 v[80:81], 0
	v_mov_b64_e32 v[82:83], 0
	v_mov_b64_e32 v[88:89], 0
	v_mov_b64_e32 v[90:91], 0
	v_mov_b64_e32 v[96:97], 0
	v_mov_b64_e32 v[98:99], 0
	v_mov_b64_e32 v[104:105], 0
	v_mov_b64_e32 v[106:107], 0
	v_mov_b64_e32 v[112:113], 0
	v_mov_b64_e32 v[114:115], 0
	v_mov_b64_e32 v[120:121], 0
	v_mov_b64_e32 v[122:123], 0
	v_mov_b64_e32 v[124:125], 0
	v_mov_b64_e32 v[126:127], 0
	s_setprio 0
	s_cmp_lt_u32 s3, 0x1000
	s_cbranch_scc1 .Lsprio_p2
	s_setprio 1

.LBB0_585:
	s_lshl_b32 s20, s49, 8
	s_ashr_i32 s21, s20, 31
	s_lshl_b64 s[20:21], s[20:21], 11
	s_add_u32 s20, s60, s20
	s_addc_u32 s21, s61, s21
	s_and_b64 s[22:23], s[6:7], exec
	s_cselect_b32 s25, s21, s27
	s_cselect_b32 s51, s20, s26
	s_ashr_i32 s19, s18, 31
	s_lshl_b64 s[22:23], s[18:19], 19
	s_add_u32 s22, s92, s22
	s_addc_u32 s23, s93, s23
	s_and_b64 s[30:31], s[6:7], exec
	s_cselect_b32 s19, s23, s29
	s_cselect_b32 s54, s22, s28
	s_add_u32 s26, s26, 0x40080
	s_addc_u32 s27, s27, 0
	s_add_u32 s55, s28, 0x100
	v_mov_b64_e32 v[0:1], 0
	s_addc_u32 s62, s29, 0
	s_mov_b32 s63, -2
	s_waitcnt lgkmcnt(0)
	v_mov_b64_e32 v[2:3], 0
	v_mov_b64_e32 v[4:5], 0
	v_mov_b64_e32 v[6:7], 0
	v_mov_b64_e32 v[16:17], 0
	v_mov_b64_e32 v[18:19], 0
	v_mov_b64_e32 v[20:21], 0
	v_mov_b64_e32 v[22:23], 0
	v_mov_b64_e32 v[32:33], 0
	v_mov_b64_e32 v[34:35], 0
	v_mov_b64_e32 v[36:37], 0
	v_mov_b64_e32 v[38:39], 0
	v_mov_b64_e32 v[48:49], 0
	v_mov_b64_e32 v[50:51], 0
	v_mov_b64_e32 v[52:53], 0
	v_mov_b64_e32 v[54:55], 0
	v_mov_b64_e32 v[8:9], 0
	v_mov_b64_e32 v[10:11], 0
	v_mov_b64_e32 v[12:13], 0
	v_mov_b64_e32 v[14:15], 0
	v_mov_b64_e32 v[24:25], 0
	v_mov_b64_e32 v[26:27], 0
	v_mov_b64_e32 v[28:29], 0
	v_mov_b64_e32 v[30:31], 0
	v_mov_b64_e32 v[40:41], 0
	v_mov_b64_e32 v[42:43], 0
	v_mov_b64_e32 v[44:45], 0
	v_mov_b64_e32 v[46:47], 0
	v_mov_b64_e32 v[56:57], 0
	v_mov_b64_e32 v[58:59], 0
	v_mov_b64_e32 v[60:61], 0
	s_waitcnt lgkmcnt(0)
	v_mov_b64_e32 v[62:63], 0
	v_mov_b64_e32 v[64:65], 0
	v_mov_b64_e32 v[66:67], 0
	v_mov_b64_e32 v[68:69], 0
	v_mov_b64_e32 v[70:71], 0
	v_mov_b64_e32 v[80:81], 0
	v_mov_b64_e32 v[82:83], 0
	v_mov_b64_e32 v[84:85], 0
	v_mov_b64_e32 v[86:87], 0
	v_mov_b64_e32 v[96:97], 0
	v_mov_b64_e32 v[98:99], 0
	v_mov_b64_e32 v[100:101], 0
	v_mov_b64_e32 v[102:103], 0
	v_mov_b64_e32 v[112:113], 0
	v_mov_b64_e32 v[114:115], 0
	v_mov_b64_e32 v[116:117], 0
	v_mov_b64_e32 v[118:119], 0
	v_mov_b64_e32 v[72:73], 0
	v_mov_b64_e32 v[74:75], 0
	v_mov_b64_e32 v[76:77], 0
	v_mov_b64_e32 v[78:79], 0
	v_mov_b64_e32 v[88:89], 0
	v_mov_b64_e32 v[90:91], 0
	v_mov_b64_e32 v[92:93], 0
	v_mov_b64_e32 v[94:95], 0
	v_mov_b64_e32 v[104:105], 0
	v_mov_b64_e32 v[106:107], 0
	v_mov_b64_e32 v[108:109], 0
	v_mov_b64_e32 v[110:111], 0
	v_mov_b64_e32 v[120:121], 0
	v_mov_b64_e32 v[122:123], 0
	v_mov_b64_e32 v[124:125], 0
	v_mov_b64_e32 v[126:127], 0
	s_setprio 0
	s_cmp_lt_u32 s3, 0x1000
	s_cbranch_scc1 .Lsprio_p5
	s_setprio 1

.LBB0_684:
	s_ashr_i32 s41, s40, 31
	s_lshl_b64 s[22:23], s[40:41], 19
	s_add_u32 s44, s56, s22
	s_addc_u32 s45, s57, s23
	s_and_b64 s[0:1], s[0:1], exec
	s_cselect_b32 s13, s45, s17
	s_cselect_b32 s21, s44, s16
	s_add_u32 s0, s18, 0x40080
	s_addc_u32 s1, s19, 0
	s_add_u32 s22, s16, 0x100
	v_mov_b64_e32 v[36:37], 0
	s_addc_u32 s23, s17, 0
	s_mov_b32 s24, -2
	v_mov_b64_e32 v[38:39], 0
	v_mov_b64_e32 v[104:105], 0
	v_mov_b64_e32 v[106:107], 0
	v_mov_b64_e32 v[0:1], 0
	v_mov_b64_e32 v[2:3], 0
	s_waitcnt vmcnt(0)
	v_mov_b64_e32 v[72:73], 0
	v_mov_b64_e32 v[74:75], 0
	v_mov_b64_e32 v[8:9], 0
	v_mov_b64_e32 v[10:11], 0
	v_mov_b64_e32 v[80:81], 0
	v_mov_b64_e32 v[82:83], 0
	v_mov_b64_e32 v[16:17], 0
	v_mov_b64_e32 v[18:19], 0
	v_mov_b64_e32 v[88:89], 0
	v_mov_b64_e32 v[90:91], 0
	v_mov_b64_e32 v[24:25], 0
	v_mov_b64_e32 v[26:27], 0
	v_mov_b64_e32 v[96:97], 0
	v_mov_b64_e32 v[98:99], 0
	v_mov_b64_e32 v[4:5], 0
	v_mov_b64_e32 v[6:7], 0
	v_mov_b64_e32 v[76:77], 0
	v_mov_b64_e32 v[78:79], 0
	v_mov_b64_e32 v[12:13], 0
	v_mov_b64_e32 v[14:15], 0
	v_mov_b64_e32 v[84:85], 0
	v_mov_b64_e32 v[86:87], 0
	v_mov_b64_e32 v[20:21], 0
	v_mov_b64_e32 v[22:23], 0
	v_mov_b64_e32 v[92:93], 0
	v_mov_b64_e32 v[94:95], 0
	v_mov_b64_e32 v[68:69], 0
	v_mov_b64_e32 v[70:71], 0
	v_mov_b64_e32 v[112:113], 0
	v_mov_b64_e32 v[114:115], 0
	v_mov_b64_e32 v[28:29], 0
	v_mov_b64_e32 v[30:31], 0
	v_mov_b64_e32 v[100:101], 0
	v_mov_b64_e32 v[102:103], 0
	v_mov_b64_e32 v[48:49], 0
	v_mov_b64_e32 v[50:51], 0
	v_mov_b64_e32 v[144:145], 0
	v_mov_b64_e32 v[146:147], 0
	v_mov_b64_e32 v[56:57], 0
	v_mov_b64_e32 v[58:59], 0
	v_mov_b64_e32 v[152:153], 0
	v_mov_b64_e32 v[154:155], 0
	v_mov_b64_e32 v[64:65], 0
	v_mov_b64_e32 v[66:67], 0
	v_mov_b64_e32 v[116:117], 0
	v_mov_b64_e32 v[118:119], 0
	v_mov_b64_e32 v[32:33], 0
	v_mov_b64_e32 v[34:35], 0
	v_mov_b64_e32 v[108:109], 0
	v_mov_b64_e32 v[110:111], 0
	v_mov_b64_e32 v[52:53], 0
	v_mov_b64_e32 v[54:55], 0
	v_mov_b64_e32 v[148:149], 0
	v_mov_b64_e32 v[150:151], 0
	v_mov_b64_e32 v[60:61], 0
	v_mov_b64_e32 v[62:63], 0
	v_mov_b64_e32 v[156:157], 0
	v_mov_b64_e32 v[158:159], 0
	s_setprio 0
	s_cmp_lt_u32 s3, 0x1000
	s_cbranch_scc1 .Lsprio_p7
	s_setprio 1

.LBB0_805:
	s_add_u32 s26, s26, 0xb0080
	s_addc_u32 s27, s27, 0
	s_add_u32 s53, s28, 0x100
	v_mov_b64_e32 v[0:1], 0
	s_addc_u32 s54, s29, 0
	s_mov_b32 s55, -2
	v_mov_b64_e32 v[2:3], 0
	v_mov_b64_e32 v[4:5], 0
	v_mov_b64_e32 v[6:7], 0
	v_mov_b64_e32 v[16:17], 0
	v_mov_b64_e32 v[18:19], 0
	v_mov_b64_e32 v[20:21], 0
	v_mov_b64_e32 v[22:23], 0
	v_mov_b64_e32 v[32:33], 0
	v_mov_b64_e32 v[34:35], 0
	v_mov_b64_e32 v[36:37], 0
	v_mov_b64_e32 v[38:39], 0
	v_mov_b64_e32 v[48:49], 0
	v_mov_b64_e32 v[50:51], 0
	v_mov_b64_e32 v[52:53], 0
	v_mov_b64_e32 v[54:55], 0
	v_mov_b64_e32 v[8:9], 0
	v_mov_b64_e32 v[10:11], 0
	v_mov_b64_e32 v[12:13], 0
	v_mov_b64_e32 v[14:15], 0
	v_mov_b64_e32 v[24:25], 0
	v_mov_b64_e32 v[26:27], 0
	v_mov_b64_e32 v[28:29], 0
	v_mov_b64_e32 v[30:31], 0
	v_mov_b64_e32 v[40:41], 0
	v_mov_b64_e32 v[42:43], 0
	v_mov_b64_e32 v[44:45], 0
	v_mov_b64_e32 v[46:47], 0
	v_mov_b64_e32 v[56:57], 0
	v_mov_b64_e32 v[58:59], 0
	v_mov_b64_e32 v[60:61], 0
	v_mov_b64_e32 v[62:63], 0
	v_mov_b64_e32 v[64:65], 0
	v_mov_b64_e32 v[66:67], 0
	v_mov_b64_e32 v[68:69], 0
	v_mov_b64_e32 v[70:71], 0
	v_mov_b64_e32 v[80:81], 0
	v_mov_b64_e32 v[82:83], 0
	v_mov_b64_e32 v[84:85], 0
	v_mov_b64_e32 v[86:87], 0
	v_mov_b64_e32 v[96:97], 0
	v_mov_b64_e32 v[98:99], 0
	v_mov_b64_e32 v[100:101], 0
	v_mov_b64_e32 v[102:103], 0
	v_mov_b64_e32 v[112:113], 0
	v_mov_b64_e32 v[114:115], 0
	v_mov_b64_e32 v[116:117], 0
	v_mov_b64_e32 v[118:119], 0
	v_mov_b64_e32 v[72:73], 0
	v_mov_b64_e32 v[74:75], 0
	v_mov_b64_e32 v[76:77], 0
	v_mov_b64_e32 v[78:79], 0
	v_mov_b64_e32 v[88:89], 0
	v_mov_b64_e32 v[90:91], 0
	v_mov_b64_e32 v[92:93], 0
	v_mov_b64_e32 v[94:95], 0
	v_mov_b64_e32 v[104:105], 0
	v_mov_b64_e32 v[106:107], 0
	v_mov_b64_e32 v[108:109], 0
	v_mov_b64_e32 v[110:111], 0
	v_mov_b64_e32 v[120:121], 0
	v_mov_b64_e32 v[122:123], 0
	v_mov_b64_e32 v[124:125], 0
	v_mov_b64_e32 v[126:127], 0
	s_setprio 0
	s_cmp_lt_u32 s36, 0x1000
	s_cbranch_scc1 .Lsprio_p11
	s_setprio 1
